# P4 EpiGate epilogue hand-written with loads two row blocks ahead, on top of the early-load chunkB version
# baseline (speedup 1.0000x reference)
; __device__ __forceinline__ void unpack8(u32x4 u, float* f) { f[0] = bflo(u.x); f[1] = bfhi(u.x); f[2] = bflo(u.y); f[3] = bfhi(u.y); f[4] = bflo(u.z); f[5] = bfhi(u.z); f[6] = bflo(u.w); f[7] = bfhi(u.w); }
; __device__ __forceinline__ float sigmoidf_(float x) { return __builtin_amdgcn_rcpf(1.f + __expf(-x)); }
; __device__ __forceinline__ unsigned cvt_pk_bf16(float lo, float hi) { unsigned r; asm volatile("v_cvt_pk_bf16_f32 %0, %1, %2" : "=v"(r) : "v"(lo), "v"(hi)); return r; }
;     __device__ __forceinline__ void operator()(const f32x4 (&acc)[2][2][4][2], const Unit& u, int wr, int wc, int fr, int fq) const {
;         const int row0 = u.pm * BM + wr * 64 + fr; const int col0 = u.pn * BM + wc * 32 + 8 * fq;
; #pragma unroll
;         for (int ai = 0; ai < 2; ++ai)
; #pragma unroll
;             for (int m = 0; m < 4; ++m) { const int row = row0 + ai * HALF + m * 16;
;                 const float rstd = __builtin_amdgcn_rsqf(rowss2[row] * (1.f / DM) + NORM_EPS);
;                 const bf16_t* hrow = h2b + (size_t)row * DM + col0; bf16_t* orow = h3b + (size_t)row * DM + col0; const bf16_t* prow = pp + (size_t)row * DM + col0; float ss = 0.f;
; #pragma unroll
;                 for (int bj = 0; bj < 2; ++bj) { const u32x4 hw = *(const u32x4*)(hrow + bj * HALF); float hf[8]; unpack8(hw, hf);
;                     const u32x4 pw = *(const u32x4*)(prow + bj * HALF); float pf[8]; unpack8(pw, pf);
;                     const f32x4 a0 = acc[ai][bj][m][0], a1 = acc[ai][bj][m][1]; f32x4 v0, v1;
; #pragma unroll
;                     for (int e = 0; e < 4; ++e) { v0[e] = hf[e] + sigmoidf_(a0[e] * rstd) * pf[e]; v1[e] = hf[4 + e] + sigmoidf_(a1[e] * rstd) * pf[4 + e]; }
;                     u32x4 w; w.x = cvt_pk_bf16(v0[0], v0[1]); w.y = cvt_pk_bf16(v0[2], v0[3]); w.z = cvt_pk_bf16(v1[0], v1[1]); w.w = cvt_pk_bf16(v1[2], v1[3]);
;                     *(u32x4*)(orow + bj * HALF) = w;
;                     ss += v0[0] * v0[0] + v0[1] * v0[1] + v0[2] * v0[2] + v0[3] * v0[3] + v1[0] * v1[0] + v1[1] * v1[1] + v1[2] * v1[2] + v1[3] * v1[3]; }
;                 ss += __shfl_xor(ss, 16); ss += __shfl_xor(ss, 32);
;                 if (fq == 0) atomicAdd(rowss3 + row, ss); }
.LBB0_610:
	v_lshl_add_u32 v154, s28, 8, v135
	v_lshl_or_b32 v158, s30, 8, v161
	v_lshlrev_b32_e32 v156, 11, v154
	v_lshl_add_u32 v156, v158, 1, v156
	v_lshlrev_b32_e32 v157, 2, v154
	v_xor_b32_e32 v154, 16, v209
	v_lshlrev_b32_e32 v154, 2, v154
	v_xor_b32_e32 v221, 32, v209
	v_lshlrev_b32_e32 v221, 2, v221
	global_load_dword v214, v157, s[10:11]
	global_load_dwordx4 v[164:167], v156, s[94:95]
	global_load_dwordx4 v[168:171], v156, s[76:77]
	global_load_dwordx4 v[172:175], v156, s[94:95] offset:256
	global_load_dwordx4 v[176:179], v156, s[76:77] offset:256
	global_load_dword v215, v157, s[10:11] offset:64
	v_add_u32_e32 v158, 0x8000, v156
	global_load_dwordx4 v[180:183], v158, s[94:95]
	global_load_dwordx4 v[184:187], v158, s[76:77]
	global_load_dwordx4 v[188:191], v158, s[94:95] offset:256
	global_load_dwordx4 v[192:195], v158, s[76:77] offset:256
	s_waitcnt vmcnt(5)
	v_fmamk_f32 v214, v214, 0x3a800000, v163
	v_rsq_f32_e32 v214, v214
	v_lshlrev_b32_e32 v152, 16, v164
	v_and_b32_e32 v153, 0xffff0000, v164
	v_lshlrev_b32_e32 v155, 16, v165
	v_and_b32_e32 v159, 0xffff0000, v165
	v_lshlrev_b32_e32 v217, 16, v166
	v_and_b32_e32 v218, 0xffff0000, v166
	v_lshlrev_b32_e32 v219, 16, v167
	v_and_b32_e32 v220, 0xffff0000, v167
	v_lshlrev_b32_e32 v164, 16, v168
	v_and_b32_e32 v168, 0xffff0000, v168
	v_lshlrev_b32_e32 v165, 16, v169
	v_and_b32_e32 v169, 0xffff0000, v169
	v_lshlrev_b32_e32 v166, 16, v170
	v_and_b32_e32 v170, 0xffff0000, v170
	v_lshlrev_b32_e32 v167, 16, v171
	v_and_b32_e32 v171, 0xffff0000, v171
	v_mul_f32_e32 v124, v124, v214
	v_mul_f32_e32 v125, v125, v214
	v_mul_f32_e32 v126, v126, v214
	v_mul_f32_e32 v127, v127, v214
	v_mul_f32_e32 v120, v120, v214
	v_mul_f32_e32 v121, v121, v214
	v_mul_f32_e32 v122, v122, v214
	v_mul_f32_e32 v123, v123, v214
	v_mul_f32_e32 v124, 0xbfb8aa3b, v124
	v_mul_f32_e32 v125, 0xbfb8aa3b, v125
	v_mul_f32_e32 v126, 0xbfb8aa3b, v126
	v_mul_f32_e32 v127, 0xbfb8aa3b, v127
	v_mul_f32_e32 v120, 0xbfb8aa3b, v120
	v_mul_f32_e32 v121, 0xbfb8aa3b, v121
	v_mul_f32_e32 v122, 0xbfb8aa3b, v122
	v_mul_f32_e32 v123, 0xbfb8aa3b, v123
	v_exp_f32_e32 v124, v124
	v_exp_f32_e32 v125, v125
	v_exp_f32_e32 v126, v126
	v_exp_f32_e32 v127, v127
	v_exp_f32_e32 v120, v120
	v_exp_f32_e32 v121, v121
	v_exp_f32_e32 v122, v122
	v_exp_f32_e32 v123, v123
	v_add_f32_e32 v124, 1.0, v124
	v_add_f32_e32 v125, 1.0, v125
	v_add_f32_e32 v126, 1.0, v126
	v_add_f32_e32 v127, 1.0, v127
	v_add_f32_e32 v120, 1.0, v120
	v_add_f32_e32 v121, 1.0, v121
	v_add_f32_e32 v122, 1.0, v122
	v_add_f32_e32 v123, 1.0, v123
	v_rcp_f32_e32 v124, v124
	v_rcp_f32_e32 v125, v125
	v_rcp_f32_e32 v126, v126
	v_rcp_f32_e32 v127, v127
	v_rcp_f32_e32 v120, v120
	v_rcp_f32_e32 v121, v121
	v_rcp_f32_e32 v122, v122
	v_rcp_f32_e32 v123, v123
	v_fmac_f32_e32 v152, v124, v164
	v_fmac_f32_e32 v153, v125, v168
	v_fmac_f32_e32 v155, v126, v165
	v_fmac_f32_e32 v159, v127, v169
	v_fmac_f32_e32 v217, v120, v166
	v_fmac_f32_e32 v218, v121, v170
	v_fmac_f32_e32 v219, v122, v167
	v_fmac_f32_e32 v220, v123, v171
	v_mul_f32_e32 v127, v153, v153
	v_fmac_f32_e32 v127, v152, v152
	v_fmac_f32_e32 v127, v155, v155
	v_fmac_f32_e32 v127, v159, v159
	v_fmac_f32_e32 v127, v217, v217
	v_fmac_f32_e32 v127, v218, v218
	v_fmac_f32_e32 v127, v219, v219
	v_fmac_f32_e32 v127, v220, v220
	v_cvt_pk_bf16_f32 v164, v152, v153
	v_cvt_pk_bf16_f32 v165, v155, v159
	v_cvt_pk_bf16_f32 v166, v217, v218
	v_cvt_pk_bf16_f32 v167, v219, v220
	global_store_dwordx4 v156, v[164:167], s[68:69]
	v_lshlrev_b32_e32 v152, 16, v172
	v_and_b32_e32 v153, 0xffff0000, v172
	v_lshlrev_b32_e32 v155, 16, v173
	v_and_b32_e32 v159, 0xffff0000, v173
	v_lshlrev_b32_e32 v217, 16, v174
	v_and_b32_e32 v218, 0xffff0000, v174
	v_lshlrev_b32_e32 v219, 16, v175
	v_and_b32_e32 v220, 0xffff0000, v175
	v_lshlrev_b32_e32 v172, 16, v176
	v_and_b32_e32 v176, 0xffff0000, v176
	v_lshlrev_b32_e32 v173, 16, v177
	v_and_b32_e32 v177, 0xffff0000, v177
	v_lshlrev_b32_e32 v174, 16, v178
	v_and_b32_e32 v178, 0xffff0000, v178
	v_lshlrev_b32_e32 v175, 16, v179
	v_and_b32_e32 v179, 0xffff0000, v179
	v_mul_f32_e32 v116, v116, v214
	v_mul_f32_e32 v117, v117, v214
	v_mul_f32_e32 v118, v118, v214
	v_mul_f32_e32 v119, v119, v214
	v_mul_f32_e32 v112, v112, v214
	v_mul_f32_e32 v113, v113, v214
	v_mul_f32_e32 v114, v114, v214
	v_mul_f32_e32 v115, v115, v214
	v_mul_f32_e32 v116, 0xbfb8aa3b, v116
	v_mul_f32_e32 v117, 0xbfb8aa3b, v117
	v_mul_f32_e32 v118, 0xbfb8aa3b, v118
	v_mul_f32_e32 v119, 0xbfb8aa3b, v119
	v_mul_f32_e32 v112, 0xbfb8aa3b, v112
	v_mul_f32_e32 v113, 0xbfb8aa3b, v113
	v_mul_f32_e32 v114, 0xbfb8aa3b, v114
	v_mul_f32_e32 v115, 0xbfb8aa3b, v115
	v_exp_f32_e32 v116, v116
	v_exp_f32_e32 v117, v117
	v_exp_f32_e32 v118, v118
	v_exp_f32_e32 v119, v119
	v_exp_f32_e32 v112, v112
	v_exp_f32_e32 v113, v113
	v_exp_f32_e32 v114, v114
	v_exp_f32_e32 v115, v115
	v_add_f32_e32 v116, 1.0, v116
	v_add_f32_e32 v117, 1.0, v117
	v_add_f32_e32 v118, 1.0, v118
	v_add_f32_e32 v119, 1.0, v119
	v_add_f32_e32 v112, 1.0, v112
	v_add_f32_e32 v113, 1.0, v113
	v_add_f32_e32 v114, 1.0, v114
	v_add_f32_e32 v115, 1.0, v115
	v_rcp_f32_e32 v116, v116
	v_rcp_f32_e32 v117, v117
	v_rcp_f32_e32 v118, v118
	v_rcp_f32_e32 v119, v119
	v_rcp_f32_e32 v112, v112
	v_rcp_f32_e32 v113, v113
	v_rcp_f32_e32 v114, v114
	v_rcp_f32_e32 v115, v115
	v_fmac_f32_e32 v152, v116, v172
	v_fmac_f32_e32 v153, v117, v176
	v_fmac_f32_e32 v155, v118, v173
	v_fmac_f32_e32 v159, v119, v177
	v_fmac_f32_e32 v217, v112, v174
	v_fmac_f32_e32 v218, v113, v178
	v_fmac_f32_e32 v219, v114, v175
	v_fmac_f32_e32 v220, v115, v179
	v_mul_f32_e32 v158, v153, v153
	v_fmac_f32_e32 v158, v152, v152
	v_fmac_f32_e32 v158, v155, v155
	v_fmac_f32_e32 v158, v159, v159
	v_fmac_f32_e32 v158, v217, v217
	v_fmac_f32_e32 v158, v218, v218
	v_fmac_f32_e32 v158, v219, v219
	v_fmac_f32_e32 v158, v220, v220
	v_add_f32_e32 v127, v127, v158
	ds_bpermute_b32 v126, v154, v127
	v_cvt_pk_bf16_f32 v172, v152, v153
	v_cvt_pk_bf16_f32 v173, v155, v159
	v_cvt_pk_bf16_f32 v174, v217, v218
	v_cvt_pk_bf16_f32 v175, v219, v220
	global_store_dwordx4 v156, v[172:175], s[68:69] offset:256
	s_nop 1
	global_load_dword v214, v157, s[10:11] offset:128
	v_add_u32_e32 v158, 0x10000, v156
	global_load_dwordx4 v[164:167], v158, s[94:95]
	global_load_dwordx4 v[168:171], v158, s[76:77]
	global_load_dwordx4 v[172:175], v158, s[94:95] offset:256
	global_load_dwordx4 v[176:179], v158, s[76:77] offset:256
	s_waitcnt vmcnt(7)
; __device__ __forceinline__ void unpack8(u32x4 u, float* f) { f[0] = bflo(u.x); f[1] = bfhi(u.x); f[2] = bflo(u.y); f[3] = bfhi(u.y); f[4] = bflo(u.z); f[5] = bfhi(u.z); f[6] = bflo(u.w); f[7] = bfhi(u.w); }
; __device__ __forceinline__ float sigmoidf_(float x) { return __builtin_amdgcn_rcpf(1.f + __expf(-x)); }
; __device__ __forceinline__ unsigned cvt_pk_bf16(float lo, float hi) { unsigned r; asm volatile("v_cvt_pk_bf16_f32 %0, %1, %2" : "=v"(r) : "v"(lo), "v"(hi)); return r; }
;     __device__ __forceinline__ void operator()(const f32x4 (&acc)[2][2][4][2], const Unit& u, int wr, int wc, int fr, int fq) const {
;     ...
;             for (int m = 0; m < 4; ++m) { const int row = row0 + ai * HALF + m * 16;
;                 const float rstd = __builtin_amdgcn_rsqf(rowss2[row] * (1.f / DM) + NORM_EPS);
;                 const bf16_t* hrow = h2b + (size_t)row * DM + col0; bf16_t* orow = h3b + (size_t)row * DM + col0; const bf16_t* prow = pp + (size_t)row * DM + col0; float ss = 0.f;
; #pragma unroll
;                 for (int bj = 0; bj < 2; ++bj) { const u32x4 hw = *(const u32x4*)(hrow + bj * HALF); float hf[8]; unpack8(hw, hf);
;                     const u32x4 pw = *(const u32x4*)(prow + bj * HALF); float pf[8]; unpack8(pw, pf);
;                     const f32x4 a0 = acc[ai][bj][m][0], a1 = acc[ai][bj][m][1]; f32x4 v0, v1;
; #pragma unroll
;                     for (int e = 0; e < 4; ++e) { v0[e] = hf[e] + sigmoidf_(a0[e] * rstd) * pf[e]; v1[e] = hf[4 + e] + sigmoidf_(a1[e] * rstd) * pf[4 + e]; }
;                     u32x4 w; w.x = cvt_pk_bf16(v0[0], v0[1]); w.y = cvt_pk_bf16(v0[2], v0[3]); w.z = cvt_pk_bf16(v1[0], v1[1]); w.w = cvt_pk_bf16(v1[2], v1[3]);
;                     *(u32x4*)(orow + bj * HALF) = w;
;                     ss += v0[0] * v0[0] + v0[1] * v0[1] + v0[2] * v0[2] + v0[3] * v0[3] + v1[0] * v1[0] + v1[1] * v1[1] + v1[2] * v1[2] + v1[3] * v1[3]; }
;                 ss += __shfl_xor(ss, 16); ss += __shfl_xor(ss, 32);
;                 if (fq == 0) atomicAdd(rowss3 + row, ss); }
	v_fmamk_f32 v215, v215, 0x3a800000, v163
	v_rsq_f32_e32 v215, v215
	v_lshlrev_b32_e32 v152, 16, v180
	v_and_b32_e32 v153, 0xffff0000, v180
	v_lshlrev_b32_e32 v155, 16, v181
	v_and_b32_e32 v159, 0xffff0000, v181
	v_lshlrev_b32_e32 v217, 16, v182
	v_and_b32_e32 v218, 0xffff0000, v182
	v_lshlrev_b32_e32 v219, 16, v183
	v_and_b32_e32 v220, 0xffff0000, v183
	v_lshlrev_b32_e32 v180, 16, v184
	v_and_b32_e32 v184, 0xffff0000, v184
	v_lshlrev_b32_e32 v181, 16, v185
	v_and_b32_e32 v185, 0xffff0000, v185
	v_lshlrev_b32_e32 v182, 16, v186
	v_and_b32_e32 v186, 0xffff0000, v186
	v_lshlrev_b32_e32 v183, 16, v187
	v_and_b32_e32 v187, 0xffff0000, v187
	v_mul_f32_e32 v108, v108, v215
	v_mul_f32_e32 v109, v109, v215
	v_mul_f32_e32 v110, v110, v215
	v_mul_f32_e32 v111, v111, v215
	v_mul_f32_e32 v104, v104, v215
	v_mul_f32_e32 v105, v105, v215
	v_mul_f32_e32 v106, v106, v215
	v_mul_f32_e32 v107, v107, v215
	v_mul_f32_e32 v108, 0xbfb8aa3b, v108
	v_mul_f32_e32 v109, 0xbfb8aa3b, v109
	v_mul_f32_e32 v110, 0xbfb8aa3b, v110
	v_mul_f32_e32 v111, 0xbfb8aa3b, v111
	v_mul_f32_e32 v104, 0xbfb8aa3b, v104
	v_mul_f32_e32 v105, 0xbfb8aa3b, v105
	v_mul_f32_e32 v106, 0xbfb8aa3b, v106
	v_mul_f32_e32 v107, 0xbfb8aa3b, v107
	v_exp_f32_e32 v108, v108
	v_exp_f32_e32 v109, v109
	v_exp_f32_e32 v110, v110
	v_exp_f32_e32 v111, v111
	v_exp_f32_e32 v104, v104
	v_exp_f32_e32 v105, v105
	v_exp_f32_e32 v106, v106
	v_exp_f32_e32 v107, v107
	v_add_f32_e32 v108, 1.0, v108
	v_add_f32_e32 v109, 1.0, v109
	v_add_f32_e32 v110, 1.0, v110
	v_add_f32_e32 v111, 1.0, v111
	v_add_f32_e32 v104, 1.0, v104
	v_add_f32_e32 v105, 1.0, v105
	v_add_f32_e32 v106, 1.0, v106
	v_add_f32_e32 v107, 1.0, v107
	v_rcp_f32_e32 v108, v108
	v_rcp_f32_e32 v109, v109
	v_rcp_f32_e32 v110, v110
	v_rcp_f32_e32 v111, v111
	v_rcp_f32_e32 v104, v104
	v_rcp_f32_e32 v105, v105
	v_rcp_f32_e32 v106, v106
	v_rcp_f32_e32 v107, v107
	v_fmac_f32_e32 v152, v108, v180
	v_fmac_f32_e32 v153, v109, v184
	v_fmac_f32_e32 v155, v110, v181
	v_fmac_f32_e32 v159, v111, v185
	v_fmac_f32_e32 v217, v104, v182
	v_fmac_f32_e32 v218, v105, v186
	v_fmac_f32_e32 v219, v106, v183
	v_fmac_f32_e32 v220, v107, v187
	v_mul_f32_e32 v111, v153, v153
	v_fmac_f32_e32 v111, v152, v152
	v_fmac_f32_e32 v111, v155, v155
	v_fmac_f32_e32 v111, v159, v159
	v_fmac_f32_e32 v111, v217, v217
	v_fmac_f32_e32 v111, v218, v218
	v_fmac_f32_e32 v111, v219, v219
	v_fmac_f32_e32 v111, v220, v220
	v_cvt_pk_bf16_f32 v180, v152, v153
	v_cvt_pk_bf16_f32 v181, v155, v159
	v_cvt_pk_bf16_f32 v182, v217, v218
	v_cvt_pk_bf16_f32 v183, v219, v220
	v_add_u32_e32 v184, 0x8000, v156
	global_store_dwordx4 v184, v[180:183], s[68:69]
	v_lshlrev_b32_e32 v152, 16, v188
	v_and_b32_e32 v153, 0xffff0000, v188
	v_lshlrev_b32_e32 v155, 16, v189
	v_and_b32_e32 v159, 0xffff0000, v189
	v_lshlrev_b32_e32 v217, 16, v190
	v_and_b32_e32 v218, 0xffff0000, v190
	v_lshlrev_b32_e32 v219, 16, v191
	v_and_b32_e32 v220, 0xffff0000, v191
	v_lshlrev_b32_e32 v188, 16, v192
	v_and_b32_e32 v192, 0xffff0000, v192
	v_lshlrev_b32_e32 v189, 16, v193
	v_and_b32_e32 v193, 0xffff0000, v193
	v_lshlrev_b32_e32 v190, 16, v194
	v_and_b32_e32 v194, 0xffff0000, v194
	v_lshlrev_b32_e32 v191, 16, v195
	v_and_b32_e32 v195, 0xffff0000, v195
	v_mul_f32_e32 v100, v100, v215
	v_mul_f32_e32 v101, v101, v215
	v_mul_f32_e32 v102, v102, v215
	v_mul_f32_e32 v103, v103, v215
	v_mul_f32_e32 v96, v96, v215
	v_mul_f32_e32 v97, v97, v215
	v_mul_f32_e32 v98, v98, v215
	v_mul_f32_e32 v99, v99, v215
	v_mul_f32_e32 v100, 0xbfb8aa3b, v100
	v_mul_f32_e32 v101, 0xbfb8aa3b, v101
	v_mul_f32_e32 v102, 0xbfb8aa3b, v102
	v_mul_f32_e32 v103, 0xbfb8aa3b, v103
	v_mul_f32_e32 v96, 0xbfb8aa3b, v96
	v_mul_f32_e32 v97, 0xbfb8aa3b, v97
	v_mul_f32_e32 v98, 0xbfb8aa3b, v98
	v_mul_f32_e32 v99, 0xbfb8aa3b, v99
	v_exp_f32_e32 v100, v100
	v_exp_f32_e32 v101, v101
	v_exp_f32_e32 v102, v102
	v_exp_f32_e32 v103, v103
	v_exp_f32_e32 v96, v96
	v_exp_f32_e32 v97, v97
	v_exp_f32_e32 v98, v98
	v_exp_f32_e32 v99, v99
	v_add_f32_e32 v100, 1.0, v100
	v_add_f32_e32 v101, 1.0, v101
	v_add_f32_e32 v102, 1.0, v102
	v_add_f32_e32 v103, 1.0, v103
	v_add_f32_e32 v96, 1.0, v96
	v_add_f32_e32 v97, 1.0, v97
	v_add_f32_e32 v98, 1.0, v98
	v_add_f32_e32 v99, 1.0, v99
	v_rcp_f32_e32 v100, v100
	v_rcp_f32_e32 v101, v101
	v_rcp_f32_e32 v102, v102
	v_rcp_f32_e32 v103, v103
	v_rcp_f32_e32 v96, v96
	v_rcp_f32_e32 v97, v97
	v_rcp_f32_e32 v98, v98
	v_rcp_f32_e32 v99, v99
	v_fmac_f32_e32 v152, v100, v188
	v_fmac_f32_e32 v153, v101, v192
	v_fmac_f32_e32 v155, v102, v189
	v_fmac_f32_e32 v159, v103, v193
	v_fmac_f32_e32 v217, v96, v190
	v_fmac_f32_e32 v218, v97, v194
	v_fmac_f32_e32 v219, v98, v191
	v_fmac_f32_e32 v220, v99, v195
	v_mul_f32_e32 v158, v153, v153
	v_fmac_f32_e32 v158, v152, v152
	v_fmac_f32_e32 v158, v155, v155
	v_fmac_f32_e32 v158, v159, v159
	v_fmac_f32_e32 v158, v217, v217
	v_fmac_f32_e32 v158, v218, v218
	v_fmac_f32_e32 v158, v219, v219
	v_fmac_f32_e32 v158, v220, v220
	v_add_f32_e32 v111, v111, v158
	s_waitcnt lgkmcnt(0)
	v_add_f32_e32 v127, v127, v126
	ds_bpermute_b32 v126, v221, v127
	ds_bpermute_b32 v110, v154, v111
	v_cvt_pk_bf16_f32 v188, v152, v153
	v_cvt_pk_bf16_f32 v189, v155, v159
	v_cvt_pk_bf16_f32 v190, v217, v218
	v_cvt_pk_bf16_f32 v191, v219, v220
	v_add_u32_e32 v192, 0x8000, v156
	global_store_dwordx4 v192, v[188:191], s[68:69] offset:256
	s_waitcnt lgkmcnt(0)
	v_add_f32_e32 v127, v127, v126
	s_mov_b64 exec, s[6:7]
	global_atomic_add_f32 v157, v127, s[12:13]
	s_mov_b64 exec, -1
	s_nop 1
	global_load_dword v215, v157, s[10:11] offset:192
	v_add_u32_e32 v158, 0x18000, v156
	global_load_dwordx4 v[180:183], v158, s[94:95]
	global_load_dwordx4 v[184:187], v158, s[76:77]
	global_load_dwordx4 v[188:191], v158, s[94:95] offset:256
	global_load_dwordx4 v[192:195], v158, s[76:77] offset:256
	s_waitcnt vmcnt(8)
; __device__ __forceinline__ void unpack8(u32x4 u, float* f) { f[0] = bflo(u.x); f[1] = bfhi(u.x); f[2] = bflo(u.y); f[3] = bfhi(u.y); f[4] = bflo(u.z); f[5] = bfhi(u.z); f[6] = bflo(u.w); f[7] = bfhi(u.w); }
; __device__ __forceinline__ float sigmoidf_(float x) { return __builtin_amdgcn_rcpf(1.f + __expf(-x)); }
; __device__ __forceinline__ unsigned cvt_pk_bf16(float lo, float hi) { unsigned r; asm volatile("v_cvt_pk_bf16_f32 %0, %1, %2" : "=v"(r) : "v"(lo), "v"(hi)); return r; }
;     __device__ __forceinline__ void operator()(const f32x4 (&acc)[2][2][4][2], const Unit& u, int wr, int wc, int fr, int fq) const {
;     ...
;             for (int m = 0; m < 4; ++m) { const int row = row0 + ai * HALF + m * 16;
;                 const float rstd = __builtin_amdgcn_rsqf(rowss2[row] * (1.f / DM) + NORM_EPS);
;                 const bf16_t* hrow = h2b + (size_t)row * DM + col0; bf16_t* orow = h3b + (size_t)row * DM + col0; const bf16_t* prow = pp + (size_t)row * DM + col0; float ss = 0.f;
; #pragma unroll
;                 for (int bj = 0; bj < 2; ++bj) { const u32x4 hw = *(const u32x4*)(hrow + bj * HALF); float hf[8]; unpack8(hw, hf);
;                     const u32x4 pw = *(const u32x4*)(prow + bj * HALF); float pf[8]; unpack8(pw, pf);
;                     const f32x4 a0 = acc[ai][bj][m][0], a1 = acc[ai][bj][m][1]; f32x4 v0, v1;
; #pragma unroll
;                     for (int e = 0; e < 4; ++e) { v0[e] = hf[e] + sigmoidf_(a0[e] * rstd) * pf[e]; v1[e] = hf[4 + e] + sigmoidf_(a1[e] * rstd) * pf[4 + e]; }
;                     u32x4 w; w.x = cvt_pk_bf16(v0[0], v0[1]); w.y = cvt_pk_bf16(v0[2], v0[3]); w.z = cvt_pk_bf16(v1[0], v1[1]); w.w = cvt_pk_bf16(v1[2], v1[3]);
;                     *(u32x4*)(orow + bj * HALF) = w;
;                     ss += v0[0] * v0[0] + v0[1] * v0[1] + v0[2] * v0[2] + v0[3] * v0[3] + v1[0] * v1[0] + v1[1] * v1[1] + v1[2] * v1[2] + v1[3] * v1[3]; }
;                 ss += __shfl_xor(ss, 16); ss += __shfl_xor(ss, 32);
;                 if (fq == 0) atomicAdd(rowss3 + row, ss); }
	v_fmamk_f32 v214, v214, 0x3a800000, v163
	v_rsq_f32_e32 v214, v214
	v_lshlrev_b32_e32 v152, 16, v164
	v_and_b32_e32 v153, 0xffff0000, v164
	v_lshlrev_b32_e32 v155, 16, v165
	v_and_b32_e32 v159, 0xffff0000, v165
	v_lshlrev_b32_e32 v217, 16, v166
	v_and_b32_e32 v218, 0xffff0000, v166
	v_lshlrev_b32_e32 v219, 16, v167
	v_and_b32_e32 v220, 0xffff0000, v167
	v_lshlrev_b32_e32 v164, 16, v168
	v_and_b32_e32 v168, 0xffff0000, v168
	v_lshlrev_b32_e32 v165, 16, v169
	v_and_b32_e32 v169, 0xffff0000, v169
	v_lshlrev_b32_e32 v166, 16, v170
	v_and_b32_e32 v170, 0xffff0000, v170
	v_lshlrev_b32_e32 v167, 16, v171
	v_and_b32_e32 v171, 0xffff0000, v171
	v_mul_f32_e32 v92, v92, v214
	v_mul_f32_e32 v93, v93, v214
	v_mul_f32_e32 v94, v94, v214
	v_mul_f32_e32 v95, v95, v214
	v_mul_f32_e32 v88, v88, v214
	v_mul_f32_e32 v89, v89, v214
	v_mul_f32_e32 v90, v90, v214
	v_mul_f32_e32 v91, v91, v214
	v_mul_f32_e32 v92, 0xbfb8aa3b, v92
	v_mul_f32_e32 v93, 0xbfb8aa3b, v93
	v_mul_f32_e32 v94, 0xbfb8aa3b, v94
	v_mul_f32_e32 v95, 0xbfb8aa3b, v95
	v_mul_f32_e32 v88, 0xbfb8aa3b, v88
	v_mul_f32_e32 v89, 0xbfb8aa3b, v89
	v_mul_f32_e32 v90, 0xbfb8aa3b, v90
	v_mul_f32_e32 v91, 0xbfb8aa3b, v91
	v_exp_f32_e32 v92, v92
	v_exp_f32_e32 v93, v93
	v_exp_f32_e32 v94, v94
	v_exp_f32_e32 v95, v95
	v_exp_f32_e32 v88, v88
	v_exp_f32_e32 v89, v89
	v_exp_f32_e32 v90, v90
	v_exp_f32_e32 v91, v91
	v_add_f32_e32 v92, 1.0, v92
	v_add_f32_e32 v93, 1.0, v93
	v_add_f32_e32 v94, 1.0, v94
	v_add_f32_e32 v95, 1.0, v95
	v_add_f32_e32 v88, 1.0, v88
	v_add_f32_e32 v89, 1.0, v89
	v_add_f32_e32 v90, 1.0, v90
	v_add_f32_e32 v91, 1.0, v91
	v_rcp_f32_e32 v92, v92
	v_rcp_f32_e32 v93, v93
	v_rcp_f32_e32 v94, v94
	v_rcp_f32_e32 v95, v95
	v_rcp_f32_e32 v88, v88
	v_rcp_f32_e32 v89, v89
	v_rcp_f32_e32 v90, v90
	v_rcp_f32_e32 v91, v91
	v_fmac_f32_e32 v152, v92, v164
	v_fmac_f32_e32 v153, v93, v168
	v_fmac_f32_e32 v155, v94, v165
	v_fmac_f32_e32 v159, v95, v169
	v_fmac_f32_e32 v217, v88, v166
	v_fmac_f32_e32 v218, v89, v170
	v_fmac_f32_e32 v219, v90, v167
	v_fmac_f32_e32 v220, v91, v171
	v_mul_f32_e32 v95, v153, v153
	v_fmac_f32_e32 v95, v152, v152
	v_fmac_f32_e32 v95, v155, v155
	v_fmac_f32_e32 v95, v159, v159
	v_fmac_f32_e32 v95, v217, v217
	v_fmac_f32_e32 v95, v218, v218
	v_fmac_f32_e32 v95, v219, v219
	v_fmac_f32_e32 v95, v220, v220
	v_cvt_pk_bf16_f32 v164, v152, v153
	v_cvt_pk_bf16_f32 v165, v155, v159
	v_cvt_pk_bf16_f32 v166, v217, v218
	v_cvt_pk_bf16_f32 v167, v219, v220
	v_add_u32_e32 v168, 0x10000, v156
	global_store_dwordx4 v168, v[164:167], s[68:69]
	v_lshlrev_b32_e32 v152, 16, v172
	v_and_b32_e32 v153, 0xffff0000, v172
	v_lshlrev_b32_e32 v155, 16, v173
	v_and_b32_e32 v159, 0xffff0000, v173
	v_lshlrev_b32_e32 v217, 16, v174
	v_and_b32_e32 v218, 0xffff0000, v174
	v_lshlrev_b32_e32 v219, 16, v175
	v_and_b32_e32 v220, 0xffff0000, v175
	v_lshlrev_b32_e32 v172, 16, v176
	v_and_b32_e32 v176, 0xffff0000, v176
	v_lshlrev_b32_e32 v173, 16, v177
	v_and_b32_e32 v177, 0xffff0000, v177
	v_lshlrev_b32_e32 v174, 16, v178
	v_and_b32_e32 v178, 0xffff0000, v178
	v_lshlrev_b32_e32 v175, 16, v179
	v_and_b32_e32 v179, 0xffff0000, v179
	v_mul_f32_e32 v84, v84, v214
	v_mul_f32_e32 v85, v85, v214
	v_mul_f32_e32 v86, v86, v214
	v_mul_f32_e32 v87, v87, v214
	v_mul_f32_e32 v80, v80, v214
	v_mul_f32_e32 v81, v81, v214
	v_mul_f32_e32 v82, v82, v214
	v_mul_f32_e32 v83, v83, v214
	v_mul_f32_e32 v84, 0xbfb8aa3b, v84
	v_mul_f32_e32 v85, 0xbfb8aa3b, v85
	v_mul_f32_e32 v86, 0xbfb8aa3b, v86
	v_mul_f32_e32 v87, 0xbfb8aa3b, v87
	v_mul_f32_e32 v80, 0xbfb8aa3b, v80
	v_mul_f32_e32 v81, 0xbfb8aa3b, v81
	v_mul_f32_e32 v82, 0xbfb8aa3b, v82
	v_mul_f32_e32 v83, 0xbfb8aa3b, v83
	v_exp_f32_e32 v84, v84
	v_exp_f32_e32 v85, v85
	v_exp_f32_e32 v86, v86
	v_exp_f32_e32 v87, v87
	v_exp_f32_e32 v80, v80
	v_exp_f32_e32 v81, v81
	v_exp_f32_e32 v82, v82
	v_exp_f32_e32 v83, v83
	v_add_f32_e32 v84, 1.0, v84
	v_add_f32_e32 v85, 1.0, v85
	v_add_f32_e32 v86, 1.0, v86
	v_add_f32_e32 v87, 1.0, v87
	v_add_f32_e32 v80, 1.0, v80
	v_add_f32_e32 v81, 1.0, v81
	v_add_f32_e32 v82, 1.0, v82
	v_add_f32_e32 v83, 1.0, v83
	v_rcp_f32_e32 v84, v84
	v_rcp_f32_e32 v85, v85
	v_rcp_f32_e32 v86, v86
	v_rcp_f32_e32 v87, v87
	v_rcp_f32_e32 v80, v80
	v_rcp_f32_e32 v81, v81
	v_rcp_f32_e32 v82, v82
	v_rcp_f32_e32 v83, v83
	v_fmac_f32_e32 v152, v84, v172
	v_fmac_f32_e32 v153, v85, v176
	v_fmac_f32_e32 v155, v86, v173
	v_fmac_f32_e32 v159, v87, v177
	v_fmac_f32_e32 v217, v80, v174
	v_fmac_f32_e32 v218, v81, v178
	v_fmac_f32_e32 v219, v82, v175
	v_fmac_f32_e32 v220, v83, v179
	v_mul_f32_e32 v158, v153, v153
	v_fmac_f32_e32 v158, v152, v152
	v_fmac_f32_e32 v158, v155, v155
	v_fmac_f32_e32 v158, v159, v159
	v_fmac_f32_e32 v158, v217, v217
	v_fmac_f32_e32 v158, v218, v218
	v_fmac_f32_e32 v158, v219, v219
	v_fmac_f32_e32 v158, v220, v220
	v_add_f32_e32 v95, v95, v158
	s_waitcnt lgkmcnt(0)
	v_add_f32_e32 v111, v111, v110
	ds_bpermute_b32 v110, v221, v111
	ds_bpermute_b32 v94, v154, v95
	v_cvt_pk_bf16_f32 v172, v152, v153
	v_cvt_pk_bf16_f32 v173, v155, v159
	v_cvt_pk_bf16_f32 v174, v217, v218
	v_cvt_pk_bf16_f32 v175, v219, v220
	v_add_u32_e32 v176, 0x10000, v156
	global_store_dwordx4 v176, v[172:175], s[68:69] offset:256
	s_waitcnt lgkmcnt(0)
	v_add_f32_e32 v111, v111, v110
	s_mov_b64 exec, s[6:7]
	global_atomic_add_f32 v157, v111, s[12:13] offset:64
	s_mov_b64 exec, -1
	s_nop 1
	global_load_dword v214, v157, s[10:11] offset:512
	v_add_u32_e32 v158, 0x40000, v156
	global_load_dwordx4 v[164:167], v158, s[94:95]
	global_load_dwordx4 v[168:171], v158, s[76:77]
	global_load_dwordx4 v[172:175], v158, s[94:95] offset:256
	global_load_dwordx4 v[176:179], v158, s[76:77] offset:256
	s_waitcnt vmcnt(8)
; __device__ __forceinline__ void unpack8(u32x4 u, float* f) { f[0] = bflo(u.x); f[1] = bfhi(u.x); f[2] = bflo(u.y); f[3] = bfhi(u.y); f[4] = bflo(u.z); f[5] = bfhi(u.z); f[6] = bflo(u.w); f[7] = bfhi(u.w); }
; __device__ __forceinline__ float sigmoidf_(float x) { return __builtin_amdgcn_rcpf(1.f + __expf(-x)); }
; __device__ __forceinline__ unsigned cvt_pk_bf16(float lo, float hi) { unsigned r; asm volatile("v_cvt_pk_bf16_f32 %0, %1, %2" : "=v"(r) : "v"(lo), "v"(hi)); return r; }
;     __device__ __forceinline__ void operator()(const f32x4 (&acc)[2][2][4][2], const Unit& u, int wr, int wc, int fr, int fq) const {
;     ...
;             for (int m = 0; m < 4; ++m) { const int row = row0 + ai * HALF + m * 16;
;                 const float rstd = __builtin_amdgcn_rsqf(rowss2[row] * (1.f / DM) + NORM_EPS);
;                 const bf16_t* hrow = h2b + (size_t)row * DM + col0; bf16_t* orow = h3b + (size_t)row * DM + col0; const bf16_t* prow = pp + (size_t)row * DM + col0; float ss = 0.f;
; #pragma unroll
;                 for (int bj = 0; bj < 2; ++bj) { const u32x4 hw = *(const u32x4*)(hrow + bj * HALF); float hf[8]; unpack8(hw, hf);
;                     const u32x4 pw = *(const u32x4*)(prow + bj * HALF); float pf[8]; unpack8(pw, pf);
;                     const f32x4 a0 = acc[ai][bj][m][0], a1 = acc[ai][bj][m][1]; f32x4 v0, v1;
; #pragma unroll
;                     for (int e = 0; e < 4; ++e) { v0[e] = hf[e] + sigmoidf_(a0[e] * rstd) * pf[e]; v1[e] = hf[4 + e] + sigmoidf_(a1[e] * rstd) * pf[4 + e]; }
;                     u32x4 w; w.x = cvt_pk_bf16(v0[0], v0[1]); w.y = cvt_pk_bf16(v0[2], v0[3]); w.z = cvt_pk_bf16(v1[0], v1[1]); w.w = cvt_pk_bf16(v1[2], v1[3]);
;                     *(u32x4*)(orow + bj * HALF) = w;
;                     ss += v0[0] * v0[0] + v0[1] * v0[1] + v0[2] * v0[2] + v0[3] * v0[3] + v1[0] * v1[0] + v1[1] * v1[1] + v1[2] * v1[2] + v1[3] * v1[3]; }
;                 ss += __shfl_xor(ss, 16); ss += __shfl_xor(ss, 32);
;                 if (fq == 0) atomicAdd(rowss3 + row, ss); }
	v_fmamk_f32 v215, v215, 0x3a800000, v163
	v_rsq_f32_e32 v215, v215
	v_lshlrev_b32_e32 v152, 16, v180
	v_and_b32_e32 v153, 0xffff0000, v180
	v_lshlrev_b32_e32 v155, 16, v181
	v_and_b32_e32 v159, 0xffff0000, v181
	v_lshlrev_b32_e32 v217, 16, v182
	v_and_b32_e32 v218, 0xffff0000, v182
	v_lshlrev_b32_e32 v219, 16, v183
	v_and_b32_e32 v220, 0xffff0000, v183
	v_lshlrev_b32_e32 v180, 16, v184
	v_and_b32_e32 v184, 0xffff0000, v184
	v_lshlrev_b32_e32 v181, 16, v185
	v_and_b32_e32 v185, 0xffff0000, v185
	v_lshlrev_b32_e32 v182, 16, v186
	v_and_b32_e32 v186, 0xffff0000, v186
	v_lshlrev_b32_e32 v183, 16, v187
	v_and_b32_e32 v187, 0xffff0000, v187
	v_mul_f32_e32 v76, v76, v215
	v_mul_f32_e32 v77, v77, v215
	v_mul_f32_e32 v78, v78, v215
	v_mul_f32_e32 v79, v79, v215
	v_mul_f32_e32 v72, v72, v215
	v_mul_f32_e32 v73, v73, v215
	v_mul_f32_e32 v74, v74, v215
	v_mul_f32_e32 v75, v75, v215
	v_mul_f32_e32 v76, 0xbfb8aa3b, v76
	v_mul_f32_e32 v77, 0xbfb8aa3b, v77
	v_mul_f32_e32 v78, 0xbfb8aa3b, v78
	v_mul_f32_e32 v79, 0xbfb8aa3b, v79
	v_mul_f32_e32 v72, 0xbfb8aa3b, v72
	v_mul_f32_e32 v73, 0xbfb8aa3b, v73
	v_mul_f32_e32 v74, 0xbfb8aa3b, v74
	v_mul_f32_e32 v75, 0xbfb8aa3b, v75
	v_exp_f32_e32 v76, v76
	v_exp_f32_e32 v77, v77
	v_exp_f32_e32 v78, v78
	v_exp_f32_e32 v79, v79
	v_exp_f32_e32 v72, v72
	v_exp_f32_e32 v73, v73
	v_exp_f32_e32 v74, v74
	v_exp_f32_e32 v75, v75
	v_add_f32_e32 v76, 1.0, v76
	v_add_f32_e32 v77, 1.0, v77
	v_add_f32_e32 v78, 1.0, v78
	v_add_f32_e32 v79, 1.0, v79
	v_add_f32_e32 v72, 1.0, v72
	v_add_f32_e32 v73, 1.0, v73
	v_add_f32_e32 v74, 1.0, v74
	v_add_f32_e32 v75, 1.0, v75
	v_rcp_f32_e32 v76, v76
	v_rcp_f32_e32 v77, v77
	v_rcp_f32_e32 v78, v78
	v_rcp_f32_e32 v79, v79
	v_rcp_f32_e32 v72, v72
	v_rcp_f32_e32 v73, v73
	v_rcp_f32_e32 v74, v74
	v_rcp_f32_e32 v75, v75
	v_fmac_f32_e32 v152, v76, v180
	v_fmac_f32_e32 v153, v77, v184
	v_fmac_f32_e32 v155, v78, v181
	v_fmac_f32_e32 v159, v79, v185
	v_fmac_f32_e32 v217, v72, v182
	v_fmac_f32_e32 v218, v73, v186
	v_fmac_f32_e32 v219, v74, v183
	v_fmac_f32_e32 v220, v75, v187
	v_mul_f32_e32 v79, v153, v153
	v_fmac_f32_e32 v79, v152, v152
	v_fmac_f32_e32 v79, v155, v155
	v_fmac_f32_e32 v79, v159, v159
	v_fmac_f32_e32 v79, v217, v217
	v_fmac_f32_e32 v79, v218, v218
	v_fmac_f32_e32 v79, v219, v219
	v_fmac_f32_e32 v79, v220, v220
	v_cvt_pk_bf16_f32 v180, v152, v153
	v_cvt_pk_bf16_f32 v181, v155, v159
	v_cvt_pk_bf16_f32 v182, v217, v218
	v_cvt_pk_bf16_f32 v183, v219, v220
	v_add_u32_e32 v184, 0x18000, v156
	global_store_dwordx4 v184, v[180:183], s[68:69]
	v_lshlrev_b32_e32 v152, 16, v188
	v_and_b32_e32 v153, 0xffff0000, v188
	v_lshlrev_b32_e32 v155, 16, v189
	v_and_b32_e32 v159, 0xffff0000, v189
	v_lshlrev_b32_e32 v217, 16, v190
	v_and_b32_e32 v218, 0xffff0000, v190
	v_lshlrev_b32_e32 v219, 16, v191
	v_and_b32_e32 v220, 0xffff0000, v191
	v_lshlrev_b32_e32 v188, 16, v192
	v_and_b32_e32 v192, 0xffff0000, v192
	v_lshlrev_b32_e32 v189, 16, v193
	v_and_b32_e32 v193, 0xffff0000, v193
	v_lshlrev_b32_e32 v190, 16, v194
	v_and_b32_e32 v194, 0xffff0000, v194
	v_lshlrev_b32_e32 v191, 16, v195
	v_and_b32_e32 v195, 0xffff0000, v195
	v_mul_f32_e32 v68, v68, v215
	v_mul_f32_e32 v69, v69, v215
	v_mul_f32_e32 v70, v70, v215
	v_mul_f32_e32 v71, v71, v215
	v_mul_f32_e32 v64, v64, v215
	v_mul_f32_e32 v65, v65, v215
	v_mul_f32_e32 v66, v66, v215
	v_mul_f32_e32 v67, v67, v215
	v_mul_f32_e32 v68, 0xbfb8aa3b, v68
	v_mul_f32_e32 v69, 0xbfb8aa3b, v69
	v_mul_f32_e32 v70, 0xbfb8aa3b, v70
	v_mul_f32_e32 v71, 0xbfb8aa3b, v71
	v_mul_f32_e32 v64, 0xbfb8aa3b, v64
	v_mul_f32_e32 v65, 0xbfb8aa3b, v65
	v_mul_f32_e32 v66, 0xbfb8aa3b, v66
	v_mul_f32_e32 v67, 0xbfb8aa3b, v67
	v_exp_f32_e32 v68, v68
	v_exp_f32_e32 v69, v69
	v_exp_f32_e32 v70, v70
	v_exp_f32_e32 v71, v71
	v_exp_f32_e32 v64, v64
	v_exp_f32_e32 v65, v65
	v_exp_f32_e32 v66, v66
	v_exp_f32_e32 v67, v67
	v_add_f32_e32 v68, 1.0, v68
	v_add_f32_e32 v69, 1.0, v69
	v_add_f32_e32 v70, 1.0, v70
	v_add_f32_e32 v71, 1.0, v71
	v_add_f32_e32 v64, 1.0, v64
	v_add_f32_e32 v65, 1.0, v65
	v_add_f32_e32 v66, 1.0, v66
	v_add_f32_e32 v67, 1.0, v67
	v_rcp_f32_e32 v68, v68
	v_rcp_f32_e32 v69, v69
	v_rcp_f32_e32 v70, v70
	v_rcp_f32_e32 v71, v71
	v_rcp_f32_e32 v64, v64
	v_rcp_f32_e32 v65, v65
	v_rcp_f32_e32 v66, v66
	v_rcp_f32_e32 v67, v67
	v_fmac_f32_e32 v152, v68, v188
	v_fmac_f32_e32 v153, v69, v192
	v_fmac_f32_e32 v155, v70, v189
	v_fmac_f32_e32 v159, v71, v193
	v_fmac_f32_e32 v217, v64, v190
	v_fmac_f32_e32 v218, v65, v194
	v_fmac_f32_e32 v219, v66, v191
	v_fmac_f32_e32 v220, v67, v195
	v_mul_f32_e32 v158, v153, v153
	v_fmac_f32_e32 v158, v152, v152
	v_fmac_f32_e32 v158, v155, v155
	v_fmac_f32_e32 v158, v159, v159
	v_fmac_f32_e32 v158, v217, v217
	v_fmac_f32_e32 v158, v218, v218
	v_fmac_f32_e32 v158, v219, v219
	v_fmac_f32_e32 v158, v220, v220
	v_add_f32_e32 v79, v79, v158
	s_waitcnt lgkmcnt(0)
	v_add_f32_e32 v95, v95, v94
	ds_bpermute_b32 v94, v221, v95
	ds_bpermute_b32 v78, v154, v79
	v_cvt_pk_bf16_f32 v188, v152, v153
	v_cvt_pk_bf16_f32 v189, v155, v159
	v_cvt_pk_bf16_f32 v190, v217, v218
	v_cvt_pk_bf16_f32 v191, v219, v220
	v_add_u32_e32 v192, 0x18000, v156
	global_store_dwordx4 v192, v[188:191], s[68:69] offset:256
	s_waitcnt lgkmcnt(0)
	v_add_f32_e32 v95, v95, v94
	s_mov_b64 exec, s[6:7]
	global_atomic_add_f32 v157, v95, s[12:13] offset:128
	s_mov_b64 exec, -1
	s_nop 1
	global_load_dword v215, v157, s[10:11] offset:576
	v_add_u32_e32 v158, 0x48000, v156
	global_load_dwordx4 v[180:183], v158, s[94:95]
	global_load_dwordx4 v[184:187], v158, s[76:77]
	global_load_dwordx4 v[188:191], v158, s[94:95] offset:256
	global_load_dwordx4 v[192:195], v158, s[76:77] offset:256
	s_waitcnt vmcnt(8)
; __device__ __forceinline__ void unpack8(u32x4 u, float* f) { f[0] = bflo(u.x); f[1] = bfhi(u.x); f[2] = bflo(u.y); f[3] = bfhi(u.y); f[4] = bflo(u.z); f[5] = bfhi(u.z); f[6] = bflo(u.w); f[7] = bfhi(u.w); }
; __device__ __forceinline__ float sigmoidf_(float x) { return __builtin_amdgcn_rcpf(1.f + __expf(-x)); }
; __device__ __forceinline__ unsigned cvt_pk_bf16(float lo, float hi) { unsigned r; asm volatile("v_cvt_pk_bf16_f32 %0, %1, %2" : "=v"(r) : "v"(lo), "v"(hi)); return r; }
;     __device__ __forceinline__ void operator()(const f32x4 (&acc)[2][2][4][2], const Unit& u, int wr, int wc, int fr, int fq) const {
;     ...
;             for (int m = 0; m < 4; ++m) { const int row = row0 + ai * HALF + m * 16;
;                 const float rstd = __builtin_amdgcn_rsqf(rowss2[row] * (1.f / DM) + NORM_EPS);
;                 const bf16_t* hrow = h2b + (size_t)row * DM + col0; bf16_t* orow = h3b + (size_t)row * DM + col0; const bf16_t* prow = pp + (size_t)row * DM + col0; float ss = 0.f;
; #pragma unroll
;                 for (int bj = 0; bj < 2; ++bj) { const u32x4 hw = *(const u32x4*)(hrow + bj * HALF); float hf[8]; unpack8(hw, hf);
;                     const u32x4 pw = *(const u32x4*)(prow + bj * HALF); float pf[8]; unpack8(pw, pf);
;                     const f32x4 a0 = acc[ai][bj][m][0], a1 = acc[ai][bj][m][1]; f32x4 v0, v1;
; #pragma unroll
;                     for (int e = 0; e < 4; ++e) { v0[e] = hf[e] + sigmoidf_(a0[e] * rstd) * pf[e]; v1[e] = hf[4 + e] + sigmoidf_(a1[e] * rstd) * pf[4 + e]; }
;                     u32x4 w; w.x = cvt_pk_bf16(v0[0], v0[1]); w.y = cvt_pk_bf16(v0[2], v0[3]); w.z = cvt_pk_bf16(v1[0], v1[1]); w.w = cvt_pk_bf16(v1[2], v1[3]);
;                     *(u32x4*)(orow + bj * HALF) = w;
;                     ss += v0[0] * v0[0] + v0[1] * v0[1] + v0[2] * v0[2] + v0[3] * v0[3] + v1[0] * v1[0] + v1[1] * v1[1] + v1[2] * v1[2] + v1[3] * v1[3]; }
;                 ss += __shfl_xor(ss, 16); ss += __shfl_xor(ss, 32);
;                 if (fq == 0) atomicAdd(rowss3 + row, ss); }
	v_fmamk_f32 v214, v214, 0x3a800000, v163
	v_rsq_f32_e32 v214, v214
	v_lshlrev_b32_e32 v152, 16, v164
	v_and_b32_e32 v153, 0xffff0000, v164
	v_lshlrev_b32_e32 v155, 16, v165
	v_and_b32_e32 v159, 0xffff0000, v165
	v_lshlrev_b32_e32 v217, 16, v166
	v_and_b32_e32 v218, 0xffff0000, v166
	v_lshlrev_b32_e32 v219, 16, v167
	v_and_b32_e32 v220, 0xffff0000, v167
	v_lshlrev_b32_e32 v164, 16, v168
	v_and_b32_e32 v168, 0xffff0000, v168
	v_lshlrev_b32_e32 v165, 16, v169
	v_and_b32_e32 v169, 0xffff0000, v169
	v_lshlrev_b32_e32 v166, 16, v170
	v_and_b32_e32 v170, 0xffff0000, v170
	v_lshlrev_b32_e32 v167, 16, v171
	v_and_b32_e32 v171, 0xffff0000, v171
	v_mul_f32_e32 v60, v60, v214
	v_mul_f32_e32 v61, v61, v214
	v_mul_f32_e32 v62, v62, v214
	v_mul_f32_e32 v63, v63, v214
	v_mul_f32_e32 v56, v56, v214
	v_mul_f32_e32 v57, v57, v214
	v_mul_f32_e32 v58, v58, v214
	v_mul_f32_e32 v59, v59, v214
	v_mul_f32_e32 v60, 0xbfb8aa3b, v60
	v_mul_f32_e32 v61, 0xbfb8aa3b, v61
	v_mul_f32_e32 v62, 0xbfb8aa3b, v62
	v_mul_f32_e32 v63, 0xbfb8aa3b, v63
	v_mul_f32_e32 v56, 0xbfb8aa3b, v56
	v_mul_f32_e32 v57, 0xbfb8aa3b, v57
	v_mul_f32_e32 v58, 0xbfb8aa3b, v58
	v_mul_f32_e32 v59, 0xbfb8aa3b, v59
	v_exp_f32_e32 v60, v60
	v_exp_f32_e32 v61, v61
	v_exp_f32_e32 v62, v62
	v_exp_f32_e32 v63, v63
	v_exp_f32_e32 v56, v56
	v_exp_f32_e32 v57, v57
	v_exp_f32_e32 v58, v58
	v_exp_f32_e32 v59, v59
	v_add_f32_e32 v60, 1.0, v60
	v_add_f32_e32 v61, 1.0, v61
	v_add_f32_e32 v62, 1.0, v62
	v_add_f32_e32 v63, 1.0, v63
	v_add_f32_e32 v56, 1.0, v56
	v_add_f32_e32 v57, 1.0, v57
	v_add_f32_e32 v58, 1.0, v58
	v_add_f32_e32 v59, 1.0, v59
	v_rcp_f32_e32 v60, v60
	v_rcp_f32_e32 v61, v61
	v_rcp_f32_e32 v62, v62
	v_rcp_f32_e32 v63, v63
	v_rcp_f32_e32 v56, v56
	v_rcp_f32_e32 v57, v57
	v_rcp_f32_e32 v58, v58
	v_rcp_f32_e32 v59, v59
	v_fmac_f32_e32 v152, v60, v164
	v_fmac_f32_e32 v153, v61, v168
	v_fmac_f32_e32 v155, v62, v165
	v_fmac_f32_e32 v159, v63, v169
	v_fmac_f32_e32 v217, v56, v166
	v_fmac_f32_e32 v218, v57, v170
	v_fmac_f32_e32 v219, v58, v167
	v_fmac_f32_e32 v220, v59, v171
	v_mul_f32_e32 v63, v153, v153
	v_fmac_f32_e32 v63, v152, v152
	v_fmac_f32_e32 v63, v155, v155
	v_fmac_f32_e32 v63, v159, v159
	v_fmac_f32_e32 v63, v217, v217
	v_fmac_f32_e32 v63, v218, v218
	v_fmac_f32_e32 v63, v219, v219
	v_fmac_f32_e32 v63, v220, v220
	v_cvt_pk_bf16_f32 v164, v152, v153
	v_cvt_pk_bf16_f32 v165, v155, v159
	v_cvt_pk_bf16_f32 v166, v217, v218
	v_cvt_pk_bf16_f32 v167, v219, v220
	v_add_u32_e32 v168, 0x40000, v156
	global_store_dwordx4 v168, v[164:167], s[68:69]
	v_lshlrev_b32_e32 v152, 16, v172
	v_and_b32_e32 v153, 0xffff0000, v172
	v_lshlrev_b32_e32 v155, 16, v173
	v_and_b32_e32 v159, 0xffff0000, v173
	v_lshlrev_b32_e32 v217, 16, v174
	v_and_b32_e32 v218, 0xffff0000, v174
	v_lshlrev_b32_e32 v219, 16, v175
	v_and_b32_e32 v220, 0xffff0000, v175
	v_lshlrev_b32_e32 v172, 16, v176
	v_and_b32_e32 v176, 0xffff0000, v176
	v_lshlrev_b32_e32 v173, 16, v177
	v_and_b32_e32 v177, 0xffff0000, v177
	v_lshlrev_b32_e32 v174, 16, v178
	v_and_b32_e32 v178, 0xffff0000, v178
	v_lshlrev_b32_e32 v175, 16, v179
	v_and_b32_e32 v179, 0xffff0000, v179
	v_mul_f32_e32 v52, v52, v214
	v_mul_f32_e32 v53, v53, v214
	v_mul_f32_e32 v54, v54, v214
	v_mul_f32_e32 v55, v55, v214
	v_mul_f32_e32 v48, v48, v214
	v_mul_f32_e32 v49, v49, v214
	v_mul_f32_e32 v50, v50, v214
	v_mul_f32_e32 v51, v51, v214
	v_mul_f32_e32 v52, 0xbfb8aa3b, v52
	v_mul_f32_e32 v53, 0xbfb8aa3b, v53
	v_mul_f32_e32 v54, 0xbfb8aa3b, v54
	v_mul_f32_e32 v55, 0xbfb8aa3b, v55
	v_mul_f32_e32 v48, 0xbfb8aa3b, v48
	v_mul_f32_e32 v49, 0xbfb8aa3b, v49
	v_mul_f32_e32 v50, 0xbfb8aa3b, v50
	v_mul_f32_e32 v51, 0xbfb8aa3b, v51
	v_exp_f32_e32 v52, v52
	v_exp_f32_e32 v53, v53
	v_exp_f32_e32 v54, v54
	v_exp_f32_e32 v55, v55
	v_exp_f32_e32 v48, v48
	v_exp_f32_e32 v49, v49
	v_exp_f32_e32 v50, v50
	v_exp_f32_e32 v51, v51
	v_add_f32_e32 v52, 1.0, v52
	v_add_f32_e32 v53, 1.0, v53
	v_add_f32_e32 v54, 1.0, v54
	v_add_f32_e32 v55, 1.0, v55
	v_add_f32_e32 v48, 1.0, v48
	v_add_f32_e32 v49, 1.0, v49
	v_add_f32_e32 v50, 1.0, v50
	v_add_f32_e32 v51, 1.0, v51
	v_rcp_f32_e32 v52, v52
	v_rcp_f32_e32 v53, v53
	v_rcp_f32_e32 v54, v54
	v_rcp_f32_e32 v55, v55
	v_rcp_f32_e32 v48, v48
	v_rcp_f32_e32 v49, v49
	v_rcp_f32_e32 v50, v50
	v_rcp_f32_e32 v51, v51
	v_fmac_f32_e32 v152, v52, v172
	v_fmac_f32_e32 v153, v53, v176
	v_fmac_f32_e32 v155, v54, v173
	v_fmac_f32_e32 v159, v55, v177
	v_fmac_f32_e32 v217, v48, v174
	v_fmac_f32_e32 v218, v49, v178
	v_fmac_f32_e32 v219, v50, v175
	v_fmac_f32_e32 v220, v51, v179
	v_mul_f32_e32 v158, v153, v153
	v_fmac_f32_e32 v158, v152, v152
	v_fmac_f32_e32 v158, v155, v155
	v_fmac_f32_e32 v158, v159, v159
	v_fmac_f32_e32 v158, v217, v217
	v_fmac_f32_e32 v158, v218, v218
	v_fmac_f32_e32 v158, v219, v219
	v_fmac_f32_e32 v158, v220, v220
	v_add_f32_e32 v63, v63, v158
	s_waitcnt lgkmcnt(0)
	v_add_f32_e32 v79, v79, v78
	ds_bpermute_b32 v78, v221, v79
	ds_bpermute_b32 v62, v154, v63
	v_cvt_pk_bf16_f32 v172, v152, v153
	v_cvt_pk_bf16_f32 v173, v155, v159
	v_cvt_pk_bf16_f32 v174, v217, v218
	v_cvt_pk_bf16_f32 v175, v219, v220
	v_add_u32_e32 v176, 0x40000, v156
	global_store_dwordx4 v176, v[172:175], s[68:69] offset:256
	s_waitcnt lgkmcnt(0)
	v_add_f32_e32 v79, v79, v78
	s_mov_b64 exec, s[6:7]
	global_atomic_add_f32 v157, v79, s[12:13] offset:192
	s_mov_b64 exec, -1
	s_nop 1
	global_load_dword v214, v157, s[10:11] offset:640
	v_add_u32_e32 v158, 0x50000, v156
	global_load_dwordx4 v[164:167], v158, s[94:95]
	global_load_dwordx4 v[168:171], v158, s[76:77]
	global_load_dwordx4 v[172:175], v158, s[94:95] offset:256
	global_load_dwordx4 v[176:179], v158, s[76:77] offset:256
	s_waitcnt vmcnt(8)
; __device__ __forceinline__ void unpack8(u32x4 u, float* f) { f[0] = bflo(u.x); f[1] = bfhi(u.x); f[2] = bflo(u.y); f[3] = bfhi(u.y); f[4] = bflo(u.z); f[5] = bfhi(u.z); f[6] = bflo(u.w); f[7] = bfhi(u.w); }
; __device__ __forceinline__ float sigmoidf_(float x) { return __builtin_amdgcn_rcpf(1.f + __expf(-x)); }
; __device__ __forceinline__ unsigned cvt_pk_bf16(float lo, float hi) { unsigned r; asm volatile("v_cvt_pk_bf16_f32 %0, %1, %2" : "=v"(r) : "v"(lo), "v"(hi)); return r; }
;     __device__ __forceinline__ void operator()(const f32x4 (&acc)[2][2][4][2], const Unit& u, int wr, int wc, int fr, int fq) const {
;     ...
;             for (int m = 0; m < 4; ++m) { const int row = row0 + ai * HALF + m * 16;
;                 const float rstd = __builtin_amdgcn_rsqf(rowss2[row] * (1.f / DM) + NORM_EPS);
;                 const bf16_t* hrow = h2b + (size_t)row * DM + col0; bf16_t* orow = h3b + (size_t)row * DM + col0; const bf16_t* prow = pp + (size_t)row * DM + col0; float ss = 0.f;
; #pragma unroll
;                 for (int bj = 0; bj < 2; ++bj) { const u32x4 hw = *(const u32x4*)(hrow + bj * HALF); float hf[8]; unpack8(hw, hf);
;                     const u32x4 pw = *(const u32x4*)(prow + bj * HALF); float pf[8]; unpack8(pw, pf);
;                     const f32x4 a0 = acc[ai][bj][m][0], a1 = acc[ai][bj][m][1]; f32x4 v0, v1;
; #pragma unroll
;                     for (int e = 0; e < 4; ++e) { v0[e] = hf[e] + sigmoidf_(a0[e] * rstd) * pf[e]; v1[e] = hf[4 + e] + sigmoidf_(a1[e] * rstd) * pf[4 + e]; }
;                     u32x4 w; w.x = cvt_pk_bf16(v0[0], v0[1]); w.y = cvt_pk_bf16(v0[2], v0[3]); w.z = cvt_pk_bf16(v1[0], v1[1]); w.w = cvt_pk_bf16(v1[2], v1[3]);
;                     *(u32x4*)(orow + bj * HALF) = w;
;                     ss += v0[0] * v0[0] + v0[1] * v0[1] + v0[2] * v0[2] + v0[3] * v0[3] + v1[0] * v1[0] + v1[1] * v1[1] + v1[2] * v1[2] + v1[3] * v1[3]; }
;                 ss += __shfl_xor(ss, 16); ss += __shfl_xor(ss, 32);
;                 if (fq == 0) atomicAdd(rowss3 + row, ss); }
	v_fmamk_f32 v215, v215, 0x3a800000, v163
	v_rsq_f32_e32 v215, v215
	v_lshlrev_b32_e32 v152, 16, v180
	v_and_b32_e32 v153, 0xffff0000, v180
	v_lshlrev_b32_e32 v155, 16, v181
	v_and_b32_e32 v159, 0xffff0000, v181
	v_lshlrev_b32_e32 v217, 16, v182
	v_and_b32_e32 v218, 0xffff0000, v182
	v_lshlrev_b32_e32 v219, 16, v183
	v_and_b32_e32 v220, 0xffff0000, v183
	v_lshlrev_b32_e32 v180, 16, v184
	v_and_b32_e32 v184, 0xffff0000, v184
	v_lshlrev_b32_e32 v181, 16, v185
	v_and_b32_e32 v185, 0xffff0000, v185
	v_lshlrev_b32_e32 v182, 16, v186
	v_and_b32_e32 v186, 0xffff0000, v186
	v_lshlrev_b32_e32 v183, 16, v187
	v_and_b32_e32 v187, 0xffff0000, v187
	v_mul_f32_e32 v44, v44, v215
	v_mul_f32_e32 v45, v45, v215
	v_mul_f32_e32 v46, v46, v215
	v_mul_f32_e32 v47, v47, v215
	v_mul_f32_e32 v40, v40, v215
	v_mul_f32_e32 v41, v41, v215
	v_mul_f32_e32 v42, v42, v215
	v_mul_f32_e32 v43, v43, v215
	v_mul_f32_e32 v44, 0xbfb8aa3b, v44
	v_mul_f32_e32 v45, 0xbfb8aa3b, v45
	v_mul_f32_e32 v46, 0xbfb8aa3b, v46
	v_mul_f32_e32 v47, 0xbfb8aa3b, v47
	v_mul_f32_e32 v40, 0xbfb8aa3b, v40
	v_mul_f32_e32 v41, 0xbfb8aa3b, v41
	v_mul_f32_e32 v42, 0xbfb8aa3b, v42
	v_mul_f32_e32 v43, 0xbfb8aa3b, v43
	v_exp_f32_e32 v44, v44
	v_exp_f32_e32 v45, v45
	v_exp_f32_e32 v46, v46
	v_exp_f32_e32 v47, v47
	v_exp_f32_e32 v40, v40
	v_exp_f32_e32 v41, v41
	v_exp_f32_e32 v42, v42
	v_exp_f32_e32 v43, v43
	v_add_f32_e32 v44, 1.0, v44
	v_add_f32_e32 v45, 1.0, v45
	v_add_f32_e32 v46, 1.0, v46
	v_add_f32_e32 v47, 1.0, v47
	v_add_f32_e32 v40, 1.0, v40
	v_add_f32_e32 v41, 1.0, v41
	v_add_f32_e32 v42, 1.0, v42
	v_add_f32_e32 v43, 1.0, v43
	v_rcp_f32_e32 v44, v44
	v_rcp_f32_e32 v45, v45
	v_rcp_f32_e32 v46, v46
	v_rcp_f32_e32 v47, v47
	v_rcp_f32_e32 v40, v40
	v_rcp_f32_e32 v41, v41
	v_rcp_f32_e32 v42, v42
	v_rcp_f32_e32 v43, v43
	v_fmac_f32_e32 v152, v44, v180
	v_fmac_f32_e32 v153, v45, v184
	v_fmac_f32_e32 v155, v46, v181
	v_fmac_f32_e32 v159, v47, v185
	v_fmac_f32_e32 v217, v40, v182
	v_fmac_f32_e32 v218, v41, v186
	v_fmac_f32_e32 v219, v42, v183
	v_fmac_f32_e32 v220, v43, v187
	v_mul_f32_e32 v47, v153, v153
	v_fmac_f32_e32 v47, v152, v152
	v_fmac_f32_e32 v47, v155, v155
	v_fmac_f32_e32 v47, v159, v159
	v_fmac_f32_e32 v47, v217, v217
	v_fmac_f32_e32 v47, v218, v218
	v_fmac_f32_e32 v47, v219, v219
	v_fmac_f32_e32 v47, v220, v220
	v_cvt_pk_bf16_f32 v180, v152, v153
	v_cvt_pk_bf16_f32 v181, v155, v159
	v_cvt_pk_bf16_f32 v182, v217, v218
	v_cvt_pk_bf16_f32 v183, v219, v220
	v_add_u32_e32 v184, 0x48000, v156
	global_store_dwordx4 v184, v[180:183], s[68:69]
	v_lshlrev_b32_e32 v152, 16, v188
	v_and_b32_e32 v153, 0xffff0000, v188
	v_lshlrev_b32_e32 v155, 16, v189
	v_and_b32_e32 v159, 0xffff0000, v189
	v_lshlrev_b32_e32 v217, 16, v190
	v_and_b32_e32 v218, 0xffff0000, v190
	v_lshlrev_b32_e32 v219, 16, v191
	v_and_b32_e32 v220, 0xffff0000, v191
	v_lshlrev_b32_e32 v188, 16, v192
	v_and_b32_e32 v192, 0xffff0000, v192
	v_lshlrev_b32_e32 v189, 16, v193
	v_and_b32_e32 v193, 0xffff0000, v193
	v_lshlrev_b32_e32 v190, 16, v194
	v_and_b32_e32 v194, 0xffff0000, v194
	v_lshlrev_b32_e32 v191, 16, v195
	v_and_b32_e32 v195, 0xffff0000, v195
	v_mul_f32_e32 v36, v36, v215
	v_mul_f32_e32 v37, v37, v215
	v_mul_f32_e32 v38, v38, v215
	v_mul_f32_e32 v39, v39, v215
	v_mul_f32_e32 v32, v32, v215
	v_mul_f32_e32 v33, v33, v215
	v_mul_f32_e32 v34, v34, v215
	v_mul_f32_e32 v35, v35, v215
	v_mul_f32_e32 v36, 0xbfb8aa3b, v36
	v_mul_f32_e32 v37, 0xbfb8aa3b, v37
	v_mul_f32_e32 v38, 0xbfb8aa3b, v38
	v_mul_f32_e32 v39, 0xbfb8aa3b, v39
	v_mul_f32_e32 v32, 0xbfb8aa3b, v32
	v_mul_f32_e32 v33, 0xbfb8aa3b, v33
	v_mul_f32_e32 v34, 0xbfb8aa3b, v34
	v_mul_f32_e32 v35, 0xbfb8aa3b, v35
	v_exp_f32_e32 v36, v36
	v_exp_f32_e32 v37, v37
	v_exp_f32_e32 v38, v38
	v_exp_f32_e32 v39, v39
	v_exp_f32_e32 v32, v32
	v_exp_f32_e32 v33, v33
	v_exp_f32_e32 v34, v34
	v_exp_f32_e32 v35, v35
	v_add_f32_e32 v36, 1.0, v36
	v_add_f32_e32 v37, 1.0, v37
	v_add_f32_e32 v38, 1.0, v38
	v_add_f32_e32 v39, 1.0, v39
	v_add_f32_e32 v32, 1.0, v32
	v_add_f32_e32 v33, 1.0, v33
	v_add_f32_e32 v34, 1.0, v34
	v_add_f32_e32 v35, 1.0, v35
	v_rcp_f32_e32 v36, v36
	v_rcp_f32_e32 v37, v37
	v_rcp_f32_e32 v38, v38
	v_rcp_f32_e32 v39, v39
	v_rcp_f32_e32 v32, v32
	v_rcp_f32_e32 v33, v33
	v_rcp_f32_e32 v34, v34
	v_rcp_f32_e32 v35, v35
	v_fmac_f32_e32 v152, v36, v188
	v_fmac_f32_e32 v153, v37, v192
	v_fmac_f32_e32 v155, v38, v189
	v_fmac_f32_e32 v159, v39, v193
	v_fmac_f32_e32 v217, v32, v190
	v_fmac_f32_e32 v218, v33, v194
	v_fmac_f32_e32 v219, v34, v191
	v_fmac_f32_e32 v220, v35, v195
	v_mul_f32_e32 v158, v153, v153
	v_fmac_f32_e32 v158, v152, v152
	v_fmac_f32_e32 v158, v155, v155
	v_fmac_f32_e32 v158, v159, v159
	v_fmac_f32_e32 v158, v217, v217
	v_fmac_f32_e32 v158, v218, v218
	v_fmac_f32_e32 v158, v219, v219
	v_fmac_f32_e32 v158, v220, v220
	v_add_f32_e32 v47, v47, v158
	s_waitcnt lgkmcnt(0)
	v_add_f32_e32 v63, v63, v62
	ds_bpermute_b32 v62, v221, v63
	ds_bpermute_b32 v46, v154, v47
	v_cvt_pk_bf16_f32 v188, v152, v153
	v_cvt_pk_bf16_f32 v189, v155, v159
	v_cvt_pk_bf16_f32 v190, v217, v218
	v_cvt_pk_bf16_f32 v191, v219, v220
	v_add_u32_e32 v192, 0x48000, v156
	global_store_dwordx4 v192, v[188:191], s[68:69] offset:256
	s_waitcnt lgkmcnt(0)
	v_add_f32_e32 v63, v63, v62
	s_mov_b64 exec, s[6:7]
	global_atomic_add_f32 v157, v63, s[12:13] offset:512
	s_mov_b64 exec, -1
	s_nop 1
	global_load_dword v215, v157, s[10:11] offset:704
	v_add_u32_e32 v158, 0x58000, v156
	global_load_dwordx4 v[180:183], v158, s[94:95]
	global_load_dwordx4 v[184:187], v158, s[76:77]
	global_load_dwordx4 v[188:191], v158, s[94:95] offset:256
	global_load_dwordx4 v[192:195], v158, s[76:77] offset:256
	s_waitcnt vmcnt(8)
; __device__ __forceinline__ void unpack8(u32x4 u, float* f) { f[0] = bflo(u.x); f[1] = bfhi(u.x); f[2] = bflo(u.y); f[3] = bfhi(u.y); f[4] = bflo(u.z); f[5] = bfhi(u.z); f[6] = bflo(u.w); f[7] = bfhi(u.w); }
; __device__ __forceinline__ float sigmoidf_(float x) { return __builtin_amdgcn_rcpf(1.f + __expf(-x)); }
; __device__ __forceinline__ unsigned cvt_pk_bf16(float lo, float hi) { unsigned r; asm volatile("v_cvt_pk_bf16_f32 %0, %1, %2" : "=v"(r) : "v"(lo), "v"(hi)); return r; }
;     __device__ __forceinline__ void operator()(const f32x4 (&acc)[2][2][4][2], const Unit& u, int wr, int wc, int fr, int fq) const {
;     ...
;             for (int m = 0; m < 4; ++m) { const int row = row0 + ai * HALF + m * 16;
;                 const float rstd = __builtin_amdgcn_rsqf(rowss2[row] * (1.f / DM) + NORM_EPS);
;                 const bf16_t* hrow = h2b + (size_t)row * DM + col0; bf16_t* orow = h3b + (size_t)row * DM + col0; const bf16_t* prow = pp + (size_t)row * DM + col0; float ss = 0.f;
; #pragma unroll
;                 for (int bj = 0; bj < 2; ++bj) { const u32x4 hw = *(const u32x4*)(hrow + bj * HALF); float hf[8]; unpack8(hw, hf);
;                     const u32x4 pw = *(const u32x4*)(prow + bj * HALF); float pf[8]; unpack8(pw, pf);
;                     const f32x4 a0 = acc[ai][bj][m][0], a1 = acc[ai][bj][m][1]; f32x4 v0, v1;
; #pragma unroll
;                     for (int e = 0; e < 4; ++e) { v0[e] = hf[e] + sigmoidf_(a0[e] * rstd) * pf[e]; v1[e] = hf[4 + e] + sigmoidf_(a1[e] * rstd) * pf[4 + e]; }
;                     u32x4 w; w.x = cvt_pk_bf16(v0[0], v0[1]); w.y = cvt_pk_bf16(v0[2], v0[3]); w.z = cvt_pk_bf16(v1[0], v1[1]); w.w = cvt_pk_bf16(v1[2], v1[3]);
;                     *(u32x4*)(orow + bj * HALF) = w;
;                     ss += v0[0] * v0[0] + v0[1] * v0[1] + v0[2] * v0[2] + v0[3] * v0[3] + v1[0] * v1[0] + v1[1] * v1[1] + v1[2] * v1[2] + v1[3] * v1[3]; }
;                 ss += __shfl_xor(ss, 16); ss += __shfl_xor(ss, 32);
;                 if (fq == 0) atomicAdd(rowss3 + row, ss); }
	v_fmamk_f32 v214, v214, 0x3a800000, v163
	v_rsq_f32_e32 v214, v214
	v_lshlrev_b32_e32 v152, 16, v164
	v_and_b32_e32 v153, 0xffff0000, v164
	v_lshlrev_b32_e32 v155, 16, v165
	v_and_b32_e32 v159, 0xffff0000, v165
	v_lshlrev_b32_e32 v217, 16, v166
	v_and_b32_e32 v218, 0xffff0000, v166
	v_lshlrev_b32_e32 v219, 16, v167
	v_and_b32_e32 v220, 0xffff0000, v167
	v_lshlrev_b32_e32 v164, 16, v168
	v_and_b32_e32 v168, 0xffff0000, v168
	v_lshlrev_b32_e32 v165, 16, v169
	v_and_b32_e32 v169, 0xffff0000, v169
	v_lshlrev_b32_e32 v166, 16, v170
	v_and_b32_e32 v170, 0xffff0000, v170
	v_lshlrev_b32_e32 v167, 16, v171
	v_and_b32_e32 v171, 0xffff0000, v171
	v_mul_f32_e32 v28, v28, v214
	v_mul_f32_e32 v29, v29, v214
	v_mul_f32_e32 v30, v30, v214
	v_mul_f32_e32 v31, v31, v214
	v_mul_f32_e32 v24, v24, v214
	v_mul_f32_e32 v25, v25, v214
	v_mul_f32_e32 v26, v26, v214
	v_mul_f32_e32 v27, v27, v214
	v_mul_f32_e32 v28, 0xbfb8aa3b, v28
	v_mul_f32_e32 v29, 0xbfb8aa3b, v29
	v_mul_f32_e32 v30, 0xbfb8aa3b, v30
	v_mul_f32_e32 v31, 0xbfb8aa3b, v31
	v_mul_f32_e32 v24, 0xbfb8aa3b, v24
	v_mul_f32_e32 v25, 0xbfb8aa3b, v25
	v_mul_f32_e32 v26, 0xbfb8aa3b, v26
	v_mul_f32_e32 v27, 0xbfb8aa3b, v27
	v_exp_f32_e32 v28, v28
	v_exp_f32_e32 v29, v29
	v_exp_f32_e32 v30, v30
	v_exp_f32_e32 v31, v31
	v_exp_f32_e32 v24, v24
	v_exp_f32_e32 v25, v25
	v_exp_f32_e32 v26, v26
	v_exp_f32_e32 v27, v27
	v_add_f32_e32 v28, 1.0, v28
	v_add_f32_e32 v29, 1.0, v29
	v_add_f32_e32 v30, 1.0, v30
	v_add_f32_e32 v31, 1.0, v31
	v_add_f32_e32 v24, 1.0, v24
	v_add_f32_e32 v25, 1.0, v25
	v_add_f32_e32 v26, 1.0, v26
	v_add_f32_e32 v27, 1.0, v27
	v_rcp_f32_e32 v28, v28
	v_rcp_f32_e32 v29, v29
	v_rcp_f32_e32 v30, v30
	v_rcp_f32_e32 v31, v31
	v_rcp_f32_e32 v24, v24
	v_rcp_f32_e32 v25, v25
	v_rcp_f32_e32 v26, v26
	v_rcp_f32_e32 v27, v27
	v_fmac_f32_e32 v152, v28, v164
	v_fmac_f32_e32 v153, v29, v168
	v_fmac_f32_e32 v155, v30, v165
	v_fmac_f32_e32 v159, v31, v169
	v_fmac_f32_e32 v217, v24, v166
	v_fmac_f32_e32 v218, v25, v170
	v_fmac_f32_e32 v219, v26, v167
	v_fmac_f32_e32 v220, v27, v171
	v_mul_f32_e32 v31, v153, v153
	v_fmac_f32_e32 v31, v152, v152
	v_fmac_f32_e32 v31, v155, v155
	v_fmac_f32_e32 v31, v159, v159
	v_fmac_f32_e32 v31, v217, v217
	v_fmac_f32_e32 v31, v218, v218
	v_fmac_f32_e32 v31, v219, v219
	v_fmac_f32_e32 v31, v220, v220
	v_cvt_pk_bf16_f32 v164, v152, v153
	v_cvt_pk_bf16_f32 v165, v155, v159
	v_cvt_pk_bf16_f32 v166, v217, v218
	v_cvt_pk_bf16_f32 v167, v219, v220
	v_add_u32_e32 v168, 0x50000, v156
	global_store_dwordx4 v168, v[164:167], s[68:69]
	v_lshlrev_b32_e32 v152, 16, v172
	v_and_b32_e32 v153, 0xffff0000, v172
	v_lshlrev_b32_e32 v155, 16, v173
	v_and_b32_e32 v159, 0xffff0000, v173
	v_lshlrev_b32_e32 v217, 16, v174
	v_and_b32_e32 v218, 0xffff0000, v174
	v_lshlrev_b32_e32 v219, 16, v175
	v_and_b32_e32 v220, 0xffff0000, v175
	v_lshlrev_b32_e32 v172, 16, v176
	v_and_b32_e32 v176, 0xffff0000, v176
	v_lshlrev_b32_e32 v173, 16, v177
	v_and_b32_e32 v177, 0xffff0000, v177
	v_lshlrev_b32_e32 v174, 16, v178
	v_and_b32_e32 v178, 0xffff0000, v178
	v_lshlrev_b32_e32 v175, 16, v179
	v_and_b32_e32 v179, 0xffff0000, v179
	v_mul_f32_e32 v20, v20, v214
	v_mul_f32_e32 v21, v21, v214
	v_mul_f32_e32 v22, v22, v214
	v_mul_f32_e32 v23, v23, v214
	v_mul_f32_e32 v16, v16, v214
	v_mul_f32_e32 v17, v17, v214
	v_mul_f32_e32 v18, v18, v214
	v_mul_f32_e32 v19, v19, v214
	v_mul_f32_e32 v20, 0xbfb8aa3b, v20
	v_mul_f32_e32 v21, 0xbfb8aa3b, v21
	v_mul_f32_e32 v22, 0xbfb8aa3b, v22
	v_mul_f32_e32 v23, 0xbfb8aa3b, v23
	v_mul_f32_e32 v16, 0xbfb8aa3b, v16
	v_mul_f32_e32 v17, 0xbfb8aa3b, v17
	v_mul_f32_e32 v18, 0xbfb8aa3b, v18
	v_mul_f32_e32 v19, 0xbfb8aa3b, v19
	v_exp_f32_e32 v20, v20
	v_exp_f32_e32 v21, v21
	v_exp_f32_e32 v22, v22
	v_exp_f32_e32 v23, v23
	v_exp_f32_e32 v16, v16
	v_exp_f32_e32 v17, v17
	v_exp_f32_e32 v18, v18
	v_exp_f32_e32 v19, v19
	v_add_f32_e32 v20, 1.0, v20
	v_add_f32_e32 v21, 1.0, v21
	v_add_f32_e32 v22, 1.0, v22
	v_add_f32_e32 v23, 1.0, v23
	v_add_f32_e32 v16, 1.0, v16
	v_add_f32_e32 v17, 1.0, v17
	v_add_f32_e32 v18, 1.0, v18
	v_add_f32_e32 v19, 1.0, v19
	v_rcp_f32_e32 v20, v20
	v_rcp_f32_e32 v21, v21
	v_rcp_f32_e32 v22, v22
	v_rcp_f32_e32 v23, v23
	v_rcp_f32_e32 v16, v16
	v_rcp_f32_e32 v17, v17
	v_rcp_f32_e32 v18, v18
	v_rcp_f32_e32 v19, v19
	v_fmac_f32_e32 v152, v20, v172
	v_fmac_f32_e32 v153, v21, v176
	v_fmac_f32_e32 v155, v22, v173
	v_fmac_f32_e32 v159, v23, v177
	v_fmac_f32_e32 v217, v16, v174
	v_fmac_f32_e32 v218, v17, v178
	v_fmac_f32_e32 v219, v18, v175
	v_fmac_f32_e32 v220, v19, v179
	v_mul_f32_e32 v158, v153, v153
	v_fmac_f32_e32 v158, v152, v152
	v_fmac_f32_e32 v158, v155, v155
	v_fmac_f32_e32 v158, v159, v159
	v_fmac_f32_e32 v158, v217, v217
	v_fmac_f32_e32 v158, v218, v218
	v_fmac_f32_e32 v158, v219, v219
	v_fmac_f32_e32 v158, v220, v220
	v_add_f32_e32 v31, v31, v158
	s_waitcnt lgkmcnt(0)
	v_add_f32_e32 v47, v47, v46
	ds_bpermute_b32 v46, v221, v47
	ds_bpermute_b32 v30, v154, v31
	v_cvt_pk_bf16_f32 v172, v152, v153
	v_cvt_pk_bf16_f32 v173, v155, v159
	v_cvt_pk_bf16_f32 v174, v217, v218
	v_cvt_pk_bf16_f32 v175, v219, v220
	v_add_u32_e32 v176, 0x50000, v156
	global_store_dwordx4 v176, v[172:175], s[68:69] offset:256
	s_waitcnt lgkmcnt(0)
	v_add_f32_e32 v47, v47, v46
	s_mov_b64 exec, s[6:7]
	global_atomic_add_f32 v157, v47, s[12:13] offset:576
	s_mov_b64 exec, -1
	s_waitcnt vmcnt(3)
; __device__ __forceinline__ void unpack8(u32x4 u, float* f) { f[0] = bflo(u.x); f[1] = bfhi(u.x); f[2] = bflo(u.y); f[3] = bfhi(u.y); f[4] = bflo(u.z); f[5] = bfhi(u.z); f[6] = bflo(u.w); f[7] = bfhi(u.w); }
; __device__ __forceinline__ float sigmoidf_(float x) { return __builtin_amdgcn_rcpf(1.f + __expf(-x)); }
; __device__ __forceinline__ unsigned cvt_pk_bf16(float lo, float hi) { unsigned r; asm volatile("v_cvt_pk_bf16_f32 %0, %1, %2" : "=v"(r) : "v"(lo), "v"(hi)); return r; }
;     __device__ __forceinline__ void operator()(const f32x4 (&acc)[2][2][4][2], const Unit& u, int wr, int wc, int fr, int fq) const {
;     ...
;             for (int m = 0; m < 4; ++m) { const int row = row0 + ai * HALF + m * 16;
;                 const float rstd = __builtin_amdgcn_rsqf(rowss2[row] * (1.f / DM) + NORM_EPS);
;                 const bf16_t* hrow = h2b + (size_t)row * DM + col0; bf16_t* orow = h3b + (size_t)row * DM + col0; const bf16_t* prow = pp + (size_t)row * DM + col0; float ss = 0.f;
; #pragma unroll
;                 for (int bj = 0; bj < 2; ++bj) { const u32x4 hw = *(const u32x4*)(hrow + bj * HALF); float hf[8]; unpack8(hw, hf);
;                     const u32x4 pw = *(const u32x4*)(prow + bj * HALF); float pf[8]; unpack8(pw, pf);
;                     const f32x4 a0 = acc[ai][bj][m][0], a1 = acc[ai][bj][m][1]; f32x4 v0, v1;
; #pragma unroll
;                     for (int e = 0; e < 4; ++e) { v0[e] = hf[e] + sigmoidf_(a0[e] * rstd) * pf[e]; v1[e] = hf[4 + e] + sigmoidf_(a1[e] * rstd) * pf[4 + e]; }
;                     u32x4 w; w.x = cvt_pk_bf16(v0[0], v0[1]); w.y = cvt_pk_bf16(v0[2], v0[3]); w.z = cvt_pk_bf16(v1[0], v1[1]); w.w = cvt_pk_bf16(v1[2], v1[3]);
;                     *(u32x4*)(orow + bj * HALF) = w;
;                     ss += v0[0] * v0[0] + v0[1] * v0[1] + v0[2] * v0[2] + v0[3] * v0[3] + v1[0] * v1[0] + v1[1] * v1[1] + v1[2] * v1[2] + v1[3] * v1[3]; }
;                 ss += __shfl_xor(ss, 16); ss += __shfl_xor(ss, 32);
;                 if (fq == 0) atomicAdd(rowss3 + row, ss); }
;     }
	v_fmamk_f32 v215, v215, 0x3a800000, v163
	v_rsq_f32_e32 v215, v215
	v_lshlrev_b32_e32 v152, 16, v180
	v_and_b32_e32 v153, 0xffff0000, v180
	v_lshlrev_b32_e32 v155, 16, v181
	v_and_b32_e32 v159, 0xffff0000, v181
	v_lshlrev_b32_e32 v217, 16, v182
	v_and_b32_e32 v218, 0xffff0000, v182
	v_lshlrev_b32_e32 v219, 16, v183
	v_and_b32_e32 v220, 0xffff0000, v183
	v_lshlrev_b32_e32 v180, 16, v184
	v_and_b32_e32 v184, 0xffff0000, v184
	v_lshlrev_b32_e32 v181, 16, v185
	v_and_b32_e32 v185, 0xffff0000, v185
	v_lshlrev_b32_e32 v182, 16, v186
	v_and_b32_e32 v186, 0xffff0000, v186
	v_lshlrev_b32_e32 v183, 16, v187
	v_and_b32_e32 v187, 0xffff0000, v187
	v_mul_f32_e32 v12, v12, v215
	v_mul_f32_e32 v13, v13, v215
	v_mul_f32_e32 v14, v14, v215
	v_mul_f32_e32 v15, v15, v215
	v_mul_f32_e32 v8, v8, v215
	v_mul_f32_e32 v9, v9, v215
	v_mul_f32_e32 v10, v10, v215
	v_mul_f32_e32 v11, v11, v215
	v_mul_f32_e32 v12, 0xbfb8aa3b, v12
	v_mul_f32_e32 v13, 0xbfb8aa3b, v13
	v_mul_f32_e32 v14, 0xbfb8aa3b, v14
	v_mul_f32_e32 v15, 0xbfb8aa3b, v15
	v_mul_f32_e32 v8, 0xbfb8aa3b, v8
	v_mul_f32_e32 v9, 0xbfb8aa3b, v9
	v_mul_f32_e32 v10, 0xbfb8aa3b, v10
	v_mul_f32_e32 v11, 0xbfb8aa3b, v11
	v_exp_f32_e32 v12, v12
	v_exp_f32_e32 v13, v13
	v_exp_f32_e32 v14, v14
	v_exp_f32_e32 v15, v15
	v_exp_f32_e32 v8, v8
	v_exp_f32_e32 v9, v9
	v_exp_f32_e32 v10, v10
	v_exp_f32_e32 v11, v11
	v_add_f32_e32 v12, 1.0, v12
	v_add_f32_e32 v13, 1.0, v13
	v_add_f32_e32 v14, 1.0, v14
	v_add_f32_e32 v15, 1.0, v15
	v_add_f32_e32 v8, 1.0, v8
	v_add_f32_e32 v9, 1.0, v9
	v_add_f32_e32 v10, 1.0, v10
	v_add_f32_e32 v11, 1.0, v11
	v_rcp_f32_e32 v12, v12
	v_rcp_f32_e32 v13, v13
	v_rcp_f32_e32 v14, v14
	v_rcp_f32_e32 v15, v15
	v_rcp_f32_e32 v8, v8
	v_rcp_f32_e32 v9, v9
	v_rcp_f32_e32 v10, v10
	v_rcp_f32_e32 v11, v11
	v_fmac_f32_e32 v152, v12, v180
	v_fmac_f32_e32 v153, v13, v184
	v_fmac_f32_e32 v155, v14, v181
	v_fmac_f32_e32 v159, v15, v185
	v_fmac_f32_e32 v217, v8, v182
	v_fmac_f32_e32 v218, v9, v186
	v_fmac_f32_e32 v219, v10, v183
	v_fmac_f32_e32 v220, v11, v187
	v_mul_f32_e32 v15, v153, v153
	v_fmac_f32_e32 v15, v152, v152
	v_fmac_f32_e32 v15, v155, v155
	v_fmac_f32_e32 v15, v159, v159
	v_fmac_f32_e32 v15, v217, v217
	v_fmac_f32_e32 v15, v218, v218
	v_fmac_f32_e32 v15, v219, v219
	v_fmac_f32_e32 v15, v220, v220
	v_cvt_pk_bf16_f32 v180, v152, v153
	v_cvt_pk_bf16_f32 v181, v155, v159
	v_cvt_pk_bf16_f32 v182, v217, v218
	v_cvt_pk_bf16_f32 v183, v219, v220
	v_add_u32_e32 v184, 0x58000, v156
	global_store_dwordx4 v184, v[180:183], s[68:69]
	v_lshlrev_b32_e32 v152, 16, v188
	v_and_b32_e32 v153, 0xffff0000, v188
	v_lshlrev_b32_e32 v155, 16, v189
	v_and_b32_e32 v159, 0xffff0000, v189
	v_lshlrev_b32_e32 v217, 16, v190
	v_and_b32_e32 v218, 0xffff0000, v190
	v_lshlrev_b32_e32 v219, 16, v191
	v_and_b32_e32 v220, 0xffff0000, v191
	v_lshlrev_b32_e32 v188, 16, v192
	v_and_b32_e32 v192, 0xffff0000, v192
	v_lshlrev_b32_e32 v189, 16, v193
	v_and_b32_e32 v193, 0xffff0000, v193
	v_lshlrev_b32_e32 v190, 16, v194
	v_and_b32_e32 v194, 0xffff0000, v194
	v_lshlrev_b32_e32 v191, 16, v195
	v_and_b32_e32 v195, 0xffff0000, v195
	v_mul_f32_e32 v4, v4, v215
	v_mul_f32_e32 v5, v5, v215
	v_mul_f32_e32 v6, v6, v215
	v_mul_f32_e32 v7, v7, v215
	v_mul_f32_e32 v0, v0, v215
	v_mul_f32_e32 v1, v1, v215
	v_mul_f32_e32 v2, v2, v215
	v_mul_f32_e32 v3, v3, v215
	v_mul_f32_e32 v4, 0xbfb8aa3b, v4
	v_mul_f32_e32 v5, 0xbfb8aa3b, v5
	v_mul_f32_e32 v6, 0xbfb8aa3b, v6
	v_mul_f32_e32 v7, 0xbfb8aa3b, v7
	v_mul_f32_e32 v0, 0xbfb8aa3b, v0
	v_mul_f32_e32 v1, 0xbfb8aa3b, v1
	v_mul_f32_e32 v2, 0xbfb8aa3b, v2
	v_mul_f32_e32 v3, 0xbfb8aa3b, v3
	v_exp_f32_e32 v4, v4
	v_exp_f32_e32 v5, v5
	v_exp_f32_e32 v6, v6
	v_exp_f32_e32 v7, v7
	v_exp_f32_e32 v0, v0
	v_exp_f32_e32 v1, v1
	v_exp_f32_e32 v2, v2
	v_exp_f32_e32 v3, v3
	v_add_f32_e32 v4, 1.0, v4
	v_add_f32_e32 v5, 1.0, v5
	v_add_f32_e32 v6, 1.0, v6
	v_add_f32_e32 v7, 1.0, v7
	v_add_f32_e32 v0, 1.0, v0
	v_add_f32_e32 v1, 1.0, v1
	v_add_f32_e32 v2, 1.0, v2
	v_add_f32_e32 v3, 1.0, v3
	v_rcp_f32_e32 v4, v4
	v_rcp_f32_e32 v5, v5
	v_rcp_f32_e32 v6, v6
	v_rcp_f32_e32 v7, v7
	v_rcp_f32_e32 v0, v0
	v_rcp_f32_e32 v1, v1
	v_rcp_f32_e32 v2, v2
	v_rcp_f32_e32 v3, v3
	v_fmac_f32_e32 v152, v4, v188
	v_fmac_f32_e32 v153, v5, v192
	v_fmac_f32_e32 v155, v6, v189
	v_fmac_f32_e32 v159, v7, v193
	v_fmac_f32_e32 v217, v0, v190
	v_fmac_f32_e32 v218, v1, v194
	v_fmac_f32_e32 v219, v2, v191
	v_fmac_f32_e32 v220, v3, v195
	v_mul_f32_e32 v158, v153, v153
	v_fmac_f32_e32 v158, v152, v152
	v_fmac_f32_e32 v158, v155, v155
	v_fmac_f32_e32 v158, v159, v159
	v_fmac_f32_e32 v158, v217, v217
	v_fmac_f32_e32 v158, v218, v218
	v_fmac_f32_e32 v158, v219, v219
	v_fmac_f32_e32 v158, v220, v220
	v_add_f32_e32 v15, v15, v158
	s_waitcnt lgkmcnt(0)
	v_add_f32_e32 v31, v31, v30
	ds_bpermute_b32 v30, v221, v31
	ds_bpermute_b32 v14, v154, v15
	v_cvt_pk_bf16_f32 v188, v152, v153
	v_cvt_pk_bf16_f32 v189, v155, v159
	v_cvt_pk_bf16_f32 v190, v217, v218
	v_cvt_pk_bf16_f32 v191, v219, v220
	v_add_u32_e32 v192, 0x58000, v156
	global_store_dwordx4 v192, v[188:191], s[68:69] offset:256
	s_waitcnt lgkmcnt(0)
	v_add_f32_e32 v31, v31, v30
	s_mov_b64 exec, s[6:7]
	global_atomic_add_f32 v157, v31, s[12:13] offset:640
	s_mov_b64 exec, -1
	s_waitcnt lgkmcnt(0)
	v_add_f32_e32 v15, v15, v14
	ds_bpermute_b32 v14, v221, v15
	s_waitcnt lgkmcnt(0)
	v_add_f32_e32 v15, v15, v14
	s_mov_b64 exec, s[6:7]
	global_atomic_add_f32 v157, v15, s[12:13] offset:704
	s_mov_b64 exec, -1
